# phase_n row loop: all 16 loads of a row issued up front (global_*), counted wait for x, one full wait instead of four serial round trips
# speedup vs baseline: 1.0034x; 1.0034x over previous
; DI unsigned pk2(float lo, float hi) { fl2_t f = {lo, hi}; bf2_t b = __builtin_convertvector(f, bf2_t); return __builtin_bit_cast(unsigned, b); }
; DI void phase_n(const Params& P, int hb) {
;     ...
;     for (int row = blockIdx.x * NWAVE + wid; row < HT; row += gridDim.x * NWAVE) {
;         const int grow = hb * HT + row; const int b = grow / SEQ;
;         const f32x4* xr = (const f32x4*)(P.x + (size_t)grow * DM);
;         f32x4 v[4]; float ss = 0.f;
; #pragma unroll
;         for (int j = 0; j < 4; ++j) { v[j] = xr[lane + 64 * j]; ss += v[j].x * v[j].x + v[j].y * v[j].y + v[j].z * v[j].z + v[j].w * v[j].w; }
;         const float rstd = rsqrtf(wave_sum(ss) * (1.f / DM) + EPS);
;         const f32x4* g = (const f32x4*)(P.g_pre);
;         const f32x4* sh = (const f32x4*)(mod + (0 * 4 + b) * 3072);
;         const f32x4* sc = (const f32x4*)(mod + (0 * 4 + b) * 3072 + 1024);
;         u32x2* o8 = (u32x2*)(Hh + (size_t)row * DM);
; #pragma unroll
;         for (int j = 0; j < 4; ++j) {
;             const int c4 = lane + 64 * j; f32x4 gg = g[c4], s1 = sc[c4], s0 = sh[c4];
;             float h0 = v[j].x * rstd * gg.x * (1.f + s1.x) + s0.x, h1 = v[j].y * rstd * gg.y * (1.f + s1.y) + s0.y;
;             float h2 = v[j].z * rstd * gg.z * (1.f + s1.z) + s0.z, h3 = v[j].w * rstd * gg.w * (1.f + s1.w) + s0.w;
;             u32x2 o = {pk2(h0, h1), pk2(h2, h3)}; o8[c4] = o;
;         }
.LBB0_73:
	v_add_u32_e32 v2, s3, v6
	v_ashrrev_i32_e32 v7, 31, v6
	v_ashrrev_i32_e32 v3, 31, v2
	v_lshlrev_b64 v[4:5], 11, v[6:7]
	v_lshlrev_b64 v[32:33], 12, v[2:3]
	v_lshrrev_b32_e32 v3, 19, v3
	v_lshl_add_u64 v[20:21], v[12:13], 0, v[4:5]
	v_lshl_add_u64 v[4:5], v[10:11], 0, v[32:33]
	global_load_dwordx4 v[32:35], v[4:5], off
	global_load_dwordx4 v[36:39], v[4:5], off offset:1024
	global_load_dwordx4 v[40:43], v[4:5], off offset:2048
	v_add_u32_e32 v7, v2, v3
	global_load_dwordx4 v[2:5], v[4:5], off offset:3072
	global_load_dwordx4 v[88:91], v[8:9], off
	global_load_dwordx4 v[92:95], v[8:9], off offset:1024
	global_load_dwordx4 v[96:99], v[8:9], off offset:2048
	global_load_dwordx4 v[100:103], v[8:9], off offset:3072
	v_ashrrev_i32_e32 v7, 13, v7
	v_mul_i32_i24_e32 v44, 0xc00, v7
	v_ashrrev_i32_e32 v45, 31, v44
	v_lshl_add_u64 v[44:45], v[44:45], 2, s[6:7]
	s_mov_b64 s[10:11], 0x1000
	v_lshl_add_u64 v[52:53], v[44:45], 0, s[10:11]
	v_lshl_add_u64 v[54:55], v[44:45], 0, v[0:1]
	v_lshl_add_u64 v[56:57], v[52:53], 0, v[0:1]
	global_load_dwordx4 v[104:107], v[56:57], off
	global_load_dwordx4 v[108:111], v[56:57], off offset:1024
	global_load_dwordx4 v[112:115], v[56:57], off offset:2048
	global_load_dwordx4 v[116:119], v[56:57], off offset:3072
	global_load_dwordx4 v[120:123], v[54:55], off
	global_load_dwordx4 v[124:127], v[54:55], off offset:1024
	global_load_dwordx4 v[28:31], v[54:55], off offset:2048
	global_load_dwordx4 v[44:47], v[54:55], off offset:3072
	v_add_u32_e32 v6, s57, v6
	s_waitcnt vmcnt(12)
	v_mov_b32_e32 v60, v33
	v_mov_b32_e32 v61, v37
	v_mov_b32_e32 v58, v32
	v_mov_b32_e32 v59, v36
	v_mov_b32_e32 v64, v41
	v_mov_b32_e32 v65, v3
	v_pk_mul_f32 v[60:61], v[60:61], v[60:61]
	v_mov_b32_e32 v62, v40
	v_mov_b32_e32 v63, v2
	v_mov_b32_e32 v66, v34
	v_mov_b32_e32 v67, v38
	v_pk_mul_f32 v[64:65], v[64:65], v[64:65]
	v_pk_fma_f32 v[58:59], v[58:59], v[58:59], v[60:61]
	v_mov_b32_e32 v68, v42
	v_mov_b32_e32 v69, v4
	v_mov_b32_e32 v70, v35
	v_mov_b32_e32 v71, v39
	v_pk_fma_f32 v[60:61], v[62:63], v[62:63], v[64:65]
	v_pk_fma_f32 v[58:59], v[66:67], v[66:67], v[58:59]
	v_mov_b32_e32 v72, v43
	v_mov_b32_e32 v73, v5
	v_pk_fma_f32 v[60:61], v[68:69], v[68:69], v[60:61]
	v_pk_fma_f32 v[58:59], v[70:71], v[70:71], v[58:59]
	v_pk_fma_f32 v[60:61], v[72:73], v[72:73], v[60:61]
	v_add_f32_e32 v7, v58, v59
	v_add_f32_e32 v7, v7, v60
	v_add_f32_e32 v7, v7, v61
	ds_bpermute_b32 v58, v22, v7
	s_waitcnt lgkmcnt(0)
	v_add_f32_e32 v7, v7, v58
	ds_bpermute_b32 v58, v23, v7
	s_waitcnt lgkmcnt(0)
	v_add_f32_e32 v7, v7, v58
	ds_bpermute_b32 v58, v24, v7
	s_waitcnt lgkmcnt(0)
	v_add_f32_e32 v7, v7, v58
	ds_bpermute_b32 v58, v25, v7
	s_waitcnt lgkmcnt(0)
	v_add_f32_e32 v7, v7, v58
	ds_bpermute_b32 v58, v26, v7
	s_waitcnt lgkmcnt(0)
	v_add_f32_e32 v7, v7, v58
	ds_bpermute_b32 v58, v27, v7
	s_waitcnt lgkmcnt(0)
	v_add_f32_e32 v7, v7, v58
	v_fmamk_f32 v7, v7, 0x3a800000, v175
	v_mul_f32_e32 v58, 0x4b800000, v7
	v_cmp_gt_f32_e32 vcc, s66, v7
	s_nop 1
	v_cndmask_b32_e32 v7, v7, v58, vcc
	v_rsq_f32_e32 v7, v7
	s_nop 0
	v_mul_f32_e32 v58, 0x45800000, v7
	v_cndmask_b32_e32 v58, v7, v58, vcc
	v_cmp_lt_i32_e32 vcc, s59, v6
	s_or_b64 s[8:9], vcc, s[8:9]
	s_waitcnt vmcnt(0)
	v_pk_mul_f32 v[32:33], v[32:33], v[58:59] op_sel_hi:[1,0]
	v_pk_mul_f32 v[34:35], v[34:35], v[58:59] op_sel_hi:[1,0]
	v_pk_mul_f32 v[36:37], v[36:37], v[58:59] op_sel_hi:[1,0]
	v_pk_mul_f32 v[38:39], v[38:39], v[58:59] op_sel_hi:[1,0]
	v_pk_mul_f32 v[40:41], v[40:41], v[58:59] op_sel_hi:[1,0]
	v_pk_mul_f32 v[42:43], v[42:43], v[58:59] op_sel_hi:[1,0]
	v_pk_mul_f32 v[2:3], v[2:3], v[58:59] op_sel_hi:[1,0]
	v_pk_mul_f32 v[4:5], v[4:5], v[58:59] op_sel_hi:[1,0]
	v_pk_add_f32 v[104:105], v[104:105], 1.0 op_sel_hi:[1,0]
	v_pk_add_f32 v[106:107], v[106:107], 1.0 op_sel_hi:[1,0]
	v_pk_add_f32 v[108:109], v[108:109], 1.0 op_sel_hi:[1,0]
	v_pk_add_f32 v[110:111], v[110:111], 1.0 op_sel_hi:[1,0]
	v_pk_add_f32 v[112:113], v[112:113], 1.0 op_sel_hi:[1,0]
	v_pk_add_f32 v[114:115], v[114:115], 1.0 op_sel_hi:[1,0]
	v_pk_add_f32 v[116:117], v[116:117], 1.0 op_sel_hi:[1,0]
	v_pk_add_f32 v[118:119], v[118:119], 1.0 op_sel_hi:[1,0]
	v_pk_mul_f32 v[88:89], v[88:89], v[32:33]
	v_pk_mul_f32 v[90:91], v[90:91], v[34:35]
	v_pk_mul_f32 v[92:93], v[92:93], v[36:37]
	v_pk_mul_f32 v[94:95], v[94:95], v[38:39]
	v_pk_mul_f32 v[96:97], v[96:97], v[40:41]
	v_pk_mul_f32 v[98:99], v[98:99], v[42:43]
	v_pk_mul_f32 v[100:101], v[100:101], v[2:3]
	v_pk_mul_f32 v[102:103], v[102:103], v[4:5]
	v_pk_fma_f32 v[88:89], v[104:105], v[88:89], v[120:121]
	v_pk_fma_f32 v[90:91], v[106:107], v[90:91], v[122:123]
	v_pk_fma_f32 v[92:93], v[108:109], v[92:93], v[124:125]
	v_pk_fma_f32 v[94:95], v[110:111], v[94:95], v[126:127]
	v_pk_fma_f32 v[96:97], v[112:113], v[96:97], v[28:29]
	v_pk_fma_f32 v[98:99], v[114:115], v[98:99], v[30:31]
	v_pk_fma_f32 v[100:101], v[116:117], v[100:101], v[44:45]
	v_pk_fma_f32 v[102:103], v[118:119], v[102:103], v[46:47]
	v_cvt_pk_bf16_f32 v60, v88, v89
	v_cvt_pk_bf16_f32 v61, v90, v91
	v_cvt_pk_bf16_f32 v62, v92, v93
	v_cvt_pk_bf16_f32 v63, v94, v95
	v_cvt_pk_bf16_f32 v64, v96, v97
	v_cvt_pk_bf16_f32 v65, v98, v99
	v_cvt_pk_bf16_f32 v66, v100, v101
	v_cvt_pk_bf16_f32 v67, v102, v103
	global_store_dwordx2 v[20:21], v[60:61], off
	global_store_dwordx2 v[20:21], v[62:63], off offset:512
	global_store_dwordx2 v[20:21], v[64:65], off offset:1024
	global_store_dwordx2 v[20:21], v[66:67], off offset:1536
	s_andn2_b64 exec, exec, s[8:9]
	s_cbranch_execnz .LBB0_73
